# SS_TAIL 530->424: four state items per idle workgroup in P12's tail (tail window may be overflowing), P11 takes 600 items
# baseline (speedup 1.0000x reference)
; #define tid opq((wave << 6) | lane_now())
; __global__ void __launch_bounds__(NTHR, 2) fwd_megakernel(Params P) {
;     ...
;         for (int item = (G == 256 ? SS_TAIL : 0) + wg; item < NS * NH; item += G) delta_sample_item<1>(P, lds, item, tid);
.LBB0_2103:
	v_readlane_b32 s4, v238, 18
	v_readlane_b32 s5, v238, 19
	s_and_b64 s[4:5], exec, s[4:5]
	s_cselect_b32 s4, 0x1a8, 0
	s_mov_b32 s3, s2
	s_cmpk_lg_u32 s78, 0x100
	s_cbranch_scc1 .Lp11_norot
	s_add_i32 s3, s2, 0xf0
	s_and_b32 s3, s3, 0xff

; __device__ __forceinline__ unsigned f2bf(float f) { return pk2(f, f) & 0xffffu; }
; __device__ __forceinline__ float rsq_f(float x) { return __builtin_amdgcn_rsqf(x); }
; __device__ __forceinline__ float sigmoid_f(float x) { return rcp_f(1.f + __expf(-x)); }
; __device__ __forceinline__ float softplus_f(float x) { return x > 20.f ? x : log1pf(__expf(x)); }
; __device__ __forceinline__ float* karg_out() { return *(volatile KAS fptr_t*)((const KAS char*)__builtin_amdgcn_kernarg_segment_ptr() + 256); }
; __device__ __forceinline__ unsigned char* karg_ws() { return *(volatile KAS ucptr_t*)((const KAS char*)__builtin_amdgcn_kernarg_segment_ptr() + 264); }
; #define INP(k) karg_in(k)
; #define lane opq(lane_now())
; #define tid opq((wave << 6) | lane_now())
; template <int MODE>
; __device__ __forceinline__ void delta_sample_item(const Params& P, LAS unsigned char* lds, int item, int tid) {
;     ...
;     pk = (rpk[v] + rpk[128 + v]) + (rpk[256 + v] + rpk[384 + v]); pq = (rpq[v] + rpq[128 + v]) + (rpq[256 + v] + rpq[384 + v]);
;     const float* ABL = (const float*)(karg_ws() + WS_ABL);
;     const float al = ABL[row * 16 + h], bl = ABL[row * 16 + 8 + h];
;     const float dc = __expf(-__expf(INP(23)[h]) * softplus_f(al + INP(24)[h])), be = sigmoid_f(bl);
;     const float delta = be * (tmp[256 + v] - dc * pk);
;     if (MODE == 0) {
;         const float o = dc * pq + kq * delta; const float so = wave_sum(o * o);
;         if (lane == 0 && wave < 2) scl[4 + wave] = so;
;         __syncthreads();
;         if (kg == 0) { bf16* zp = (bf16*)(karg_ws() + WS_Z + 5 * ZB) + row * D + h * 128 + v;
;             *zp = (bf16)f2bf(o * rsq_f((scl[4] + scl[5]) * (1.f / 128.f) + EPS) * INP(25)[v] * bf2f(*zp)); } }
;     else { float* So = karg_out() + O_SS + ((size_t)(bs * NH + h) * 128 + kg * 32) * 128 + v;
; #pragma unroll
;         for (int j = 0; j < 32; ++j) __builtin_nontemporal_store(dc * S[j] + (tmp[128 + kg * 32 + j] * sk) * delta, So + (size_t)j * 128); }
; __global__ void __launch_bounds__(NTHR, 2) fwd_megakernel(Params P) {
;     ...
;       if (G == 256 && wg >= 150) for (int item = wg - 150; item < SS_TAIL; item += 106) delta_sample_item<1>(P, lds, item, tid); }
.LBB0_2226:
	s_cmpk_gt_i32 s2, 0x95
	v_readlane_b32 s6, v238, 18
	s_cselect_b64 s[4:5], -1, 0
	v_readlane_b32 s7, v238, 19
	s_and_b64 s[4:5], s[4:5], s[6:7]
	s_cmpk_lt_u32 s2, 0x23e
	s_cselect_b64 s[6:7], -1, 0
	s_and_b64 s[4:5], s[4:5], s[6:7]
	s_andn2_b64 vcc, exec, s[4:5]
	s_cbranch_vccnz .LBB0_2248
	s_ashr_i32 s3, s2, 31
	s_add_i32 s18, s2, 0xffffff00
	s_lshl_b64 s[4:5], s[2:3], 16
	s_add_u32 s10, s4, 0x3d8be00
	s_addc_u32 s11, s5, 0
	s_movk_i32 s3, 0x180
	s_mov_b32 s19, 0x2040000
	s_mov_b32 s13, 0
	v_mov_b32_e32 v1, 0
	s_mov_b32 s20, 0x90c0000
	s_mov_b32 s21, 0x9000
	s_movk_i32 s22, 0x3000
	s_movk_i32 s23, 0x6000
	s_mov_b32 s24, 0xfb915000
	s_mov_b32 s25, 0xfb916000
	s_mov_b32 s26, 0xfb917000
	s_mov_b32 s27, 0xfb918000
	v_mov_b32_e32 v12, 0x2e00000
	s_mov_b32 s28, 0x41a00000
	s_mov_b32 s29, 0x3f2aaaab
	v_mov_b32_e32 v13, 0x3ecc95a3
	s_mov_b32 s30, 0x3f317218
	s_mov_b32 s31, 0x7f800000
	s_mov_b32 s34, 0x33800000
	s_movk_i32 s35, 0xd000
	s_movk_i32 s36, 0xe000
	s_movk_i32 s37, 0xf000
	v_mov_b32_e32 v14, 0x300
	v_mov_b32_e32 v2, 0x3f317218
	v_mov_b32_e32 v15, 0x7f800000
	v_mov_b32_e32 v16, 0x7fc00000
	v_mov_b32_e32 v17, 0xff800000
	s_branch .LBB0_2229
.LBB0_2228:
	v_mul_f32_e32 v51, 0x3fb8aa3b, v51
	v_exp_f32_e32 v51, v51
	v_add_f32_e32 v8, v8, v9
	v_add_f32_e32 v9, v10, v11
	v_mul_f32_e32 v10, 0xbfb8aa3b, v50
	v_exp_f32_e32 v10, v10
	v_mul_f32_e32 v3, v3, v51
	v_mul_f32_e32 v3, 0xbfb8aa3b, v3
	ds_read_b32 v4, v4 offset:1024
	v_exp_f32_e32 v3, v3
	v_add_f32_e32 v10, 1.0, v10
	v_rcp_f32_e32 v10, v10
	v_add_f32_e32 v8, v8, v9
	s_load_dwordx2 s[4:5], s[0:1], 0x100
	s_waitcnt lgkmcnt(0)
	v_fma_f32 v4, -v8, v3, v4
	v_mul_f32_e32 v4, v10, v4
	ds_read_b128 v[8:11], v25 offset:512
	ds_read_b128 v[50:53], v25 offset:528
	ds_read_b128 v[54:57], v25 offset:544
	v_lshl_add_u64 v[6:7], s[4:5], 0, v[6:7]
	v_lshl_add_u64 v[58:59], v[6:7], 0, s[10:11]
	s_add_u32 s10, s10, 0x6a0000
	s_waitcnt lgkmcnt(2)
	v_mul_f32_e32 v6, v5, v8
	v_mul_f32_e32 v8, v6, v4
	v_add_co_u32_e32 v6, vcc, s35, v58
	v_fmac_f32_e32 v8, v49, v3
	s_nop 0
	v_addc_co_u32_e32 v7, vcc, -1, v59, vcc
	global_store_dword v[6:7], v8, off offset:-3584 nt
	v_mul_f32_e32 v8, v5, v9
	v_mul_f32_e32 v8, v4, v8
	v_fmac_f32_e32 v8, v48, v3
	global_store_dword v[6:7], v8, off offset:-3072 nt
	v_mul_f32_e32 v8, v5, v10
	v_mul_f32_e32 v8, v4, v8
	v_fmac_f32_e32 v8, v47, v3
	global_store_dword v[6:7], v8, off offset:-2560 nt
	v_mul_f32_e32 v8, v5, v11
	v_mul_f32_e32 v8, v4, v8
	v_fmac_f32_e32 v8, v46, v3
	global_store_dword v[6:7], v8, off offset:-2048 nt
	s_waitcnt lgkmcnt(1)
	v_mul_f32_e32 v8, v5, v50
	v_mul_f32_e32 v8, v4, v8
	v_fmac_f32_e32 v8, v45, v3
	global_store_dword v[6:7], v8, off offset:-1536 nt
	v_mul_f32_e32 v8, v5, v51
	v_mul_f32_e32 v8, v4, v8
	v_fmac_f32_e32 v8, v44, v3
	global_store_dword v[6:7], v8, off offset:-1024 nt
	v_mul_f32_e32 v8, v5, v52
	v_mul_f32_e32 v8, v4, v8
	v_fmac_f32_e32 v8, v42, v3
	global_store_dword v[6:7], v8, off offset:-512 nt
	v_mul_f32_e32 v6, v5, v53
	v_mul_f32_e32 v6, v4, v6
	v_add_co_u32_e32 v10, vcc, s36, v58
	s_waitcnt lgkmcnt(0)
	v_mul_f32_e32 v42, v5, v54
	v_fmac_f32_e32 v6, v43, v3
	v_addc_co_u32_e32 v11, vcc, -1, v59, vcc
	v_mul_f32_e32 v42, v4, v42
	global_store_dword v[10:11], v6, off offset:-4096 nt
	ds_read_b128 v[6:9], v25 offset:560
	v_fmac_f32_e32 v42, v41, v3
	v_mul_f32_e32 v41, v5, v55
	v_mul_f32_e32 v41, v4, v41
	v_fmac_f32_e32 v41, v40, v3
	v_mul_f32_e32 v40, v5, v56
	v_mul_f32_e32 v40, v4, v40
	v_fmac_f32_e32 v40, v39, v3
	v_mul_f32_e32 v39, v5, v57
	v_mul_f32_e32 v39, v4, v39
	s_waitcnt lgkmcnt(0)
	v_mul_f32_e32 v6, v5, v6
	v_fmac_f32_e32 v39, v38, v3
	v_mul_f32_e32 v6, v4, v6
	global_store_dword v[10:11], v42, off offset:-3584 nt
	global_store_dword v[10:11], v41, off offset:-3072 nt
	global_store_dword v[10:11], v40, off offset:-2560 nt
	global_store_dword v[10:11], v39, off offset:-2048 nt
	v_fmac_f32_e32 v6, v37, v3
	ds_read_b128 v[38:41], v25 offset:576
	ds_read_b128 v[42:45], v25 offset:592
	ds_read_b128 v[46:49], v25 offset:608
	global_store_dword v[10:11], v6, off offset:-1536 nt
	v_mul_f32_e32 v6, v5, v7
	v_mul_f32_e32 v6, v4, v6
	v_fmac_f32_e32 v6, v36, v3
	global_store_dword v[10:11], v6, off offset:-1024 nt
	v_mul_f32_e32 v6, v5, v8
	v_mul_f32_e32 v6, v4, v6
	v_fmac_f32_e32 v6, v35, v3
	global_store_dword v[10:11], v6, off offset:-512 nt
	v_mul_f32_e32 v6, v5, v9
	v_mul_f32_e32 v6, v4, v6
	v_fmac_f32_e32 v6, v33, v3
	global_store_dword v[10:11], v6, off nt
	s_waitcnt lgkmcnt(2)
	v_mul_f32_e32 v6, v5, v38
	v_mul_f32_e32 v8, v4, v6
	v_add_co_u32_e32 v6, vcc, s37, v58
	v_fmac_f32_e32 v8, v34, v3
	s_nop 0
	v_addc_co_u32_e32 v7, vcc, -1, v59, vcc
	global_store_dword v[6:7], v8, off offset:-3584 nt
	v_mul_f32_e32 v8, v5, v39
	v_mul_f32_e32 v8, v4, v8
	v_fmac_f32_e32 v8, v32, v3
	global_store_dword v[6:7], v8, off offset:-3072 nt
	v_mul_f32_e32 v8, v5, v40
	v_mul_f32_e32 v8, v4, v8
	v_fmac_f32_e32 v8, v31, v3
	global_store_dword v[6:7], v8, off offset:-2560 nt
	v_mul_f32_e32 v8, v5, v41
	v_mul_f32_e32 v8, v4, v8
	v_fmac_f32_e32 v8, v30, v3
	global_store_dword v[6:7], v8, off offset:-2048 nt
	s_waitcnt lgkmcnt(1)
	v_mul_f32_e32 v8, v5, v42
	v_mul_f32_e32 v8, v4, v8
	v_fmac_f32_e32 v8, v29, v3
	global_store_dword v[6:7], v8, off offset:-1536 nt
	v_mul_f32_e32 v8, v5, v43
	v_mul_f32_e32 v8, v4, v8
	v_fmac_f32_e32 v8, v28, v3
	global_store_dword v[6:7], v8, off offset:-1024 nt
	v_mul_f32_e32 v8, v5, v44
	v_mul_f32_e32 v8, v4, v8
	v_fmac_f32_e32 v8, v26, v3
	global_store_dword v[6:7], v8, off offset:-512 nt
	v_mul_f32_e32 v6, v5, v45
	v_mul_f32_e32 v6, v4, v6
	v_fmac_f32_e32 v6, v27, v3
	global_store_dword v[58:59], v6, off offset:-4096 nt
	ds_read_b128 v[6:9], v25 offset:624
	s_waitcnt lgkmcnt(1)
	v_mul_f32_e32 v10, v5, v46
	v_mul_f32_e32 v10, v4, v10
	v_fmac_f32_e32 v10, v24, v3
	global_store_dword v[58:59], v10, off offset:-3584 nt
	v_mul_f32_e32 v10, v5, v47
	s_waitcnt lgkmcnt(0)
	v_mul_f32_e32 v6, v5, v6
	v_mul_f32_e32 v10, v4, v10
	v_mul_f32_e32 v6, v4, v6
	v_fmac_f32_e32 v10, v23, v3
	v_fmac_f32_e32 v6, v20, v3
	global_store_dword v[58:59], v10, off offset:-3072 nt
	v_mul_f32_e32 v10, v5, v48
	global_store_dword v[58:59], v6, off offset:-1536 nt
	v_mul_f32_e32 v6, v5, v7
	v_mul_f32_e32 v10, v4, v10
	v_mul_f32_e32 v6, v4, v6
	v_fmac_f32_e32 v10, v22, v3
	v_fmac_f32_e32 v6, v19, v3
	global_store_dword v[58:59], v10, off offset:-2560 nt
	v_mul_f32_e32 v10, v5, v49
	global_store_dword v[58:59], v6, off offset:-1024 nt
	v_mul_f32_e32 v6, v5, v8
	v_mul_f32_e32 v5, v5, v9
	v_mul_f32_e32 v10, v4, v10
	v_mul_f32_e32 v6, v4, v6
	v_mul_f32_e32 v4, v4, v5
	s_addc_u32 s11, s11, 0
	v_fmac_f32_e32 v10, v21, v3
	v_fmac_f32_e32 v6, v18, v3
	v_fmac_f32_e32 v4, v0, v3
	s_cmpk_lt_i32 s18, 0x13e
	global_store_dword v[58:59], v10, off offset:-2048 nt
	global_store_dword v[58:59], v6, off offset:-512 nt
	global_store_dword v[58:59], v4, off nt
	s_barrier
	s_cbranch_scc0 .LBB0_2248
